# P3: odd blocks run conv+window before the sample items, even blocks after (bandwidth-bound and latency-bound sections overlap across blocks); built on v45 (no attn_sample pre-issue)
# baseline (speedup 1.0000x reference)
; DEV float bf2f(unsigned h) { return __uint_as_float(h << 16); }
; DEV void ret_sample_item(const Params& p, int l, int item, unsigned char* smem) {
;     ...
;   {
;     const int i = tid >> 6, d = tid & 63;
;     qs[tid] = bf2f(Z[(rowbase + i) * NIN + RQ + h * 64 + d]);
;     ks[tid] = bf2f(Z[(rowbase + i) * NIN + RK + h * 64 + d]) * 0.125f;
; #pragma unroll
;     for (int it = 0; it < 2; ++it) { const int idx = tid + it * 512, ii = idx >> 7, e = idx & 127; vs[idx] = bf2f(Z[(rowbase + ii) * NIN + RV + h * 128 + e]); }
;   }
;   __syncthreads();
;   if (tid < 64) {
;     const int i = tid >> 3, j = tid & 7;
;     float dsum = 0.f;
;     for (int d = 0; d < 64; ++d) dsum += qs[i * 64 + d] * ks[j * 64 + d];
;     inn[tid] = (i >= j) ? dsum * __expf(lg * (float)(i - j)) : 0.f;
;   }
;   {
;     const int e = tid & 127, dg = tid >> 7;
;     const float* S0 = p.in[I_SRET] + (size_t)((l * 128 + b) * 4 + h) * 8192;
;     float* Sn = p.out + O_RETS + (size_t)((l * 128 + b) * 4 + h) * 8192;
;     const float cdec = __expf(lg * 8.0f);
;     float po[8];
; #pragma unroll
;     for (int i = 0; i < 8; ++i) po[i] = 0.f;
;     float kv[8];
; #pragma unroll
;     for (int j = 0; j < 8; ++j) kv[j] = __expf(lg * (float)(7 - j)) * vs[j * 128 + e];
;     float s0v[16];
; #pragma unroll
;     for (int dd = 0; dd < 16; ++dd) s0v[dd] = S0[(dg * 16 + dd) * 128 + e];
; DEV void conv_and_window(const Params& p, int l) {
;     ...
;   for (int c = gtid; c < 4 * 128 * 128 * 2; c += gstride) {
;     const int col = c & 127, j = (c >> 7) & 127, b = (c >> 14) & 3, kv = c >> 16;
;     const float v = bf2f(Z[((size_t)b * SEQ + SEQ - 128 + j) * NIN + (kv ? AV : AK) + col]);
.LBB0_329:
	s_andn2_b64 vcc, exec, s[0:1]
	s_cbranch_vccnz .LBB0_422
	v_lshl_add_u32 v240, s74, 9, v171
	v_bfe_u32 v241, v240, 7, 7
	v_bfe_u32 v242, v240, 14, 2
	v_cmp_gt_u32_e32 vcc, 0x10000, v240
	v_lshl_or_b32 v241, v242, 12, v241
	v_mov_b32_e32 v243, 0
	v_cndmask_b32_e32 v242, v210, v211, vcc
	v_mul_u32_u24_e32 v241, 0x1b00, v241
	v_lshl_add_u64 v[244:245], s[30:31], 0, v[242:243]
	v_lshlrev_b32_e32 v242, 1, v241
	v_lshl_add_u64 v[244:245], v[244:245], 0, v[242:243]
	v_and_b32_e32 v242, 0x7f, v171
	v_lshlrev_b32_e32 v242, 1, v242
	v_lshl_add_u64 v[244:245], v[244:245], 0, v[242:243]
	v_mov_b32_e32 v242, 0x3450000
	v_lshl_add_u64 v[244:245], v[244:245], 0, v[242:243]
	global_load_ushort v246, v[244:245], off
	s_and_b32 s45, s74, 3
	s_lshl_b32 s44, s74, 1
	s_and_b32 s44, s44, -8
	s_add_u32 s44, s44, 0x4000
	s_lshl_b32 s52, s45, 7
	s_mov_b32 s53, 0
	v_ashrrev_i32_e32 v234, 6, v171
	v_add_u32_e32 v234, s44, v234
	v_mov_b64_e32 v[236:237], s[30:31]
	v_mov_b32_e32 v239, 0
	v_and_b32_e32 v235, 63, v171
	v_mad_u64_u32 v[236:237], vcc, v234, s95, v[236:237]
	v_lshlrev_b32_e32 v238, 1, v235
	v_lshl_add_u64 v[236:237], v[236:237], 0, s[52:53]
	v_lshl_add_u64 v[236:237], v[236:237], 0, v[238:239]
	global_load_ushort v240, v[236:237], off
	global_load_ushort v241, v[236:237], off offset:512
	v_lshl_add_u64 v[236:237], v[236:237], 0, s[52:53]
	global_load_ushort v244, v[236:237], off offset:2048
	global_load_ushort v245, v[236:237], off offset:2176
	v_ashrrev_i32_e32 v234, 7, v171
	v_add_u32_e32 v235, 0x200, v171
	v_add_u32_e32 v234, s44, v234
	v_ashrrev_i32_e32 v235, 7, v235
	v_mov_b64_e32 v[236:237], s[30:31]
	v_add_u32_e32 v235, s44, v235
	v_mad_u64_u32 v[236:237], vcc, v234, s95, v[236:237]
	v_mov_b64_e32 v[238:239], s[30:31]
	s_lshl_b32 s52, s45, 8
	v_mad_u64_u32 v[238:239], vcc, v235, s95, v[238:239]
	v_and_b32_e32 v234, 0x7f, v171
	v_lshlrev_b32_e32 v234, 1, v234
	v_mov_b32_e32 v235, 0
	v_lshl_add_u64 v[236:237], v[236:237], 0, s[52:53]
	v_lshl_add_u64 v[238:239], v[238:239], 0, s[52:53]
	v_lshl_add_u64 v[236:237], v[236:237], 0, v[234:235]
	v_lshl_add_u64 v[238:239], v[238:239], 0, v[234:235]
	global_load_ushort v242, v[236:237], off offset:1024
	global_load_ushort v243, v[238:239], off offset:1024
	v_readlane_b32 s45, v248, 43
	s_and_b32 s44, s74, -4
	s_nop 0
	s_lshl_b32 s45, s45, 9
	s_add_i32 s44, s44, s45
	s_and_b32 s45, s74, 3
	s_or_b32 s44, s44, s45
	v_readlane_b32 s52, v248, 28
	v_readlane_b32 s53, v248, 29
	s_ashr_i32 s45, s44, 31
	s_lshl_b64 s[44:45], s[44:45], 15
	v_ashrrev_i32_e32 v236, 7, v171
	v_and_b32_e32 v237, 0x7f, v171
	v_lshl_or_b32 v236, v236, 11, v237
	v_ashrrev_i32_e32 v237, 31, v236
	v_lshlrev_b64 v[236:237], 2, v[236:237]
	s_add_u32 s44, s52, s44
	s_addc_u32 s45, s53, s45
	v_lshl_add_u64 v[234:235], s[44:45], 0, v[236:237]
	s_add_u32 s44, s44, 0x1000
	s_addc_u32 s45, s45, 0
	v_lshl_add_u64 v[238:239], s[44:45], 0, v[236:237]
	global_load_dword v218, v[234:235], off
	global_load_dword v219, v[234:235], off offset:512
	global_load_dword v220, v[234:235], off offset:1024
	global_load_dword v221, v[234:235], off offset:1536
	global_load_dword v222, v[234:235], off offset:2048
	global_load_dword v223, v[234:235], off offset:2560
	global_load_dword v224, v[234:235], off offset:3072
	global_load_dword v225, v[234:235], off offset:3584
	global_load_dword v226, v[238:239], off
	global_load_dword v227, v[238:239], off offset:512
	global_load_dword v228, v[238:239], off offset:1024
	global_load_dword v229, v[238:239], off offset:1536
	global_load_dword v230, v[238:239], off offset:2048
	global_load_dword v231, v[238:239], off offset:2560
	global_load_dword v232, v[238:239], off offset:3072
	global_load_dword v233, v[238:239], off offset:3584
	s_mov_b32 s4, s74
	v_mov_b32_e32 v0, v171
	s_mov_b32 s13, 0x20000
	v_lshl_add_u32 v4, s4, 9, v0
	v_cmp_gt_i32_e32 vcc, s13, v4
	s_and_saveexec_b64 s[0:1], vcc
	v_readlane_b32 s9, v249, 34
	v_readlane_b32 s12, v249, 59
	s_mov_b32 s14, 0x10000
	s_mov_b32 s15, 0xc2fc0000
	s_mov_b32 s16, 0x3f2aaaab
	s_mov_b32 s17, 0x3f317218
	s_mov_b32 s18, 0x33800000
	s_mov_b32 s19, 0x40000
	s_mov_b32 s20, 0x48000
	s_mov_b32 s21, 0x50000
	s_mov_b32 s26, 0x58000
	s_mov_b32 s35, 0x88000
	s_mov_b32 s40, 0x1ffff
	s_cbranch_execz .LBB0_333
	s_add_u32 s2, s28, 0x3500000
	v_readlane_b32 s36, v248, 43
	v_lshlrev_b32_e32 v0, 7, v0
	s_addc_u32 s3, s29, 0
	s_lshl_b32 s6, s36, 4
	v_lshl_add_u32 v5, s4, 16, v0
	s_mov_b64 s[4:5], 0
	v_readlane_b32 s37, v248, 44

; DEV int bidx() { int t = blockIdx.x; asm volatile("" : "+s"(t)); return t; }
; DEV void run_phase(const Params& pin, int ph, unsigned char* smem) {
;     ...
;       ret_scan(p, l);
;       for (int it = bidx(); it < 768; it += gridDim.x) {
;         if (it < 512) ret_sample_item(p, l, it, smem);
;         else attn_sample_item(p, l, it - 512, smem);
.LBB0_333:
	s_mov_b32 s34, 0x20000
	s_or_b64 exec, exec, s[0:1]
	s_bitcmp1_b32 s74, 0
	s_cbranch_scc1 .LBB0_364
.Lp3_items:
	s_mov_b32 s12, s74
	s_mov_b32 s41, 0x42fc0000
	s_cmpk_gt_i32 s12, 0x2ff
	s_cbranch_scc1 .Lp3_after_items
	v_readlane_b32 s0, v248, 43
	s_lshl_b32 s13, s0, 7
	s_add_u32 s14, s22, 0x6608000
	s_addc_u32 s15, s23, 0
	s_add_u32 s16, s22, 0x7608000
	s_addc_u32 s17, s23, 0
	s_lshl_b32 s18, s0, 3
	s_lshl_b32 s19, s0, 9
	s_add_u32 s20, s22, 0x4608000
	s_addc_u32 s21, s23, 0
	v_readlane_b32 s1, v248, 44
	s_branch .LBB0_337

; DEV int bidx() { int t = blockIdx.x; asm volatile("" : "+s"(t)); return t; }
; DEV void run_phase(const Params& pin, int ph, unsigned char* smem) {
;     ...
;       for (int it = bidx(); it < 768; it += gridDim.x) {
;         if (it < 512) ret_sample_item(p, l, it, smem);
;         else attn_sample_item(p, l, it - 512, smem);
;       }
;       conv_and_window(p, l);
.Lp3_after_items:
	s_bitcmp1_b32 s74, 0
	s_cbranch_scc1 .LBB0_422

; DEV int bidx() { int t = blockIdx.x; asm volatile("" : "+s"(t)); return t; }
; DEV void run_phase(const Params& pin, int ph, unsigned char* smem) {
;     ...
;       for (int it = bidx(); it < 768; it += gridDim.x) {
;         if (it < 512) ret_sample_item(p, l, it, smem);
;         else attn_sample_item(p, l, it - 512, smem);
;       }
;       conv_and_window(p, l);
.LBB0_421:
	s_or_b64 exec, exec, s[2:3]
	s_bitcmp1_b32 s74, 0
	s_cbranch_scc1 .Lp3_items
